# GQA attention loop: merged QK+load+PV scheduling region, LDS prefetch with counted waits, one barrier per tile instead of two
# speedup vs baseline: 1.0056x; 1.0056x over previous
.LBB0_739:
	ds_read_b128 v[64:67], v200 offset:49152
	ds_read_b128 v[68:71], v200 offset:57344
	ds_read_b128 v[236:239], v208 offset:49152
	ds_read_b128 v[240:243], v208 offset:57344
	ds_read_b128 v[244:247], v207 offset:49152
	ds_read_b128 v[248:251], v207 offset:57344
	s_add_i32 s6, s14, -3
	s_waitcnt lgkmcnt(5)
	v_mfma_f32_32x32x16_bf16 v[80:95], v[64:67], v[124:127], 0
	v_exp_f32_e32 v158, v158
	v_exp_f32_e32 v159, v159
	v_add_f32_e32 v210, 0, v162
	s_waitcnt lgkmcnt(4)
	v_mfma_f32_32x32x16_bf16 v[64:79], v[68:71], v[124:127], 0
	v_exp_f32_e32 v156, v156
	v_exp_f32_e32 v157, v157
	v_add_f32_e32 v210, v216, v210
	s_waitcnt lgkmcnt(3)
	v_mfma_f32_32x32x16_bf16 v[80:95], v[236:239], v[120:123], v[80:95]
	ds_read_b128 v[236:239], v206 offset:49152
	v_exp_f32_e32 v150, v150
	v_exp_f32_e32 v151, v151
	v_add_f32_e32 v210, v163, v210
	s_waitcnt lgkmcnt(3)
	v_mfma_f32_32x32x16_bf16 v[64:79], v[240:243], v[120:123], v[64:79]
	ds_read_b128 v[240:243], v206 offset:57344
	v_exp_f32_e32 v148, v148
	v_exp_f32_e32 v149, v149
	v_add_f32_e32 v210, v177, v210
	s_waitcnt lgkmcnt(3)
	v_mfma_f32_32x32x16_bf16 v[80:95], v[244:247], v[116:119], v[80:95]
	ds_read_b128 v[244:247], v205 offset:49152
	v_exp_f32_e32 v146, v146
	v_exp_f32_e32 v147, v147
	v_add_f32_e32 v210, v164, v210
	s_waitcnt lgkmcnt(3)
	v_mfma_f32_32x32x16_bf16 v[64:79], v[248:251], v[116:119], v[64:79]
	ds_read_b128 v[248:251], v205 offset:57344
	v_exp_f32_e32 v160, v160
	v_exp_f32_e32 v161, v161
	v_add_f32_e32 v210, v176, v210
	s_waitcnt lgkmcnt(3)
	v_mfma_f32_32x32x16_bf16 v[80:95], v[236:239], v[112:115], v[80:95]
	ds_read_b128 v[236:239], v204 offset:49152
	v_exp_f32_e32 v154, v154
	v_exp_f32_e32 v155, v155
	v_add_f32_e32 v210, v165, v210
	s_waitcnt lgkmcnt(3)
	v_mfma_f32_32x32x16_bf16 v[64:79], v[240:243], v[112:115], v[64:79]
	ds_read_b128 v[240:243], v204 offset:57344
	v_exp_f32_e32 v152, v152
	v_exp_f32_e32 v153, v153
	v_add_f32_e32 v210, v175, v210
	s_waitcnt lgkmcnt(3)
	v_mfma_f32_32x32x16_bf16 v[80:95], v[244:247], v[108:111], v[80:95]
	ds_read_b128 v[244:247], v202 offset:49152
	v_add_f32_e32 v210, v166, v210
	v_add_f32_e32 v210, v173, v210
	v_add_f32_e32 v210, v167, v210
	v_add_f32_e32 v210, v172, v210
	v_add_f32_e32 v210, v168, v210
	s_waitcnt lgkmcnt(3)
	v_mfma_f32_32x32x16_bf16 v[64:79], v[248:251], v[108:111], v[64:79]
	ds_read_b128 v[248:251], v202 offset:57344
	v_add_f32_e32 v210, v171, v210
	v_add_f32_e32 v210, v169, v210
	v_add_f32_e32 v210, v170, v210
	v_add_f32_e32 v210, v158, v210
	v_add_f32_e32 v210, v159, v210
	s_waitcnt lgkmcnt(3)
	v_mfma_f32_32x32x16_bf16 v[80:95], v[236:239], v[104:107], v[80:95]
	ds_read_b128 v[236:239], v201 offset:49152
	v_add_f32_e32 v210, v156, v210
	v_add_f32_e32 v210, v157, v210
	v_add_f32_e32 v210, v150, v210
	v_add_f32_e32 v210, v151, v210
	v_add_f32_e32 v210, v148, v210
	s_waitcnt lgkmcnt(3)
	v_mfma_f32_32x32x16_bf16 v[64:79], v[240:243], v[104:107], v[64:79]
	ds_read_b128 v[240:243], v201 offset:57344
	v_add_f32_e32 v210, v149, v210
	v_add_f32_e32 v210, v146, v210
	v_add_f32_e32 v210, v147, v210
	v_add_f32_e32 v210, v160, v210
	v_add_f32_e32 v210, v161, v210
	s_waitcnt lgkmcnt(3)
	v_mfma_f32_32x32x16_bf16 v[80:95], v[244:247], v[100:103], v[80:95]
	v_add_f32_e32 v210, v154, v210
	v_add_f32_e32 v210, v155, v210
	v_add_f32_e32 v210, v152, v210
	v_add_f32_e32 v210, v153, v210
	v_mov_b32_e32 v211, v210
	s_waitcnt lgkmcnt(2)
	v_mfma_f32_32x32x16_bf16 v[64:79], v[248:251], v[100:103], v[64:79]
	v_cvt_pk_bf16_f32 v162, v162, v216
	v_cvt_pk_bf16_f32 v163, v163, v177
	v_cvt_pk_bf16_f32 v164, v164, v176
	v_permlane32_swap_b32_e32 v210, v211
	v_cvt_pk_bf16_f32 v165, v165, v175
	ds_read_b64_tr_b16 v[216:217], v193 offset:0
	ds_read_b64_tr_b16 v[218:219], v193 offset:0x800
	ds_read_b64_tr_b16 v[220:221], v193 offset:0x1000
	ds_read_b64_tr_b16 v[222:223], v193 offset:0x1800
	ds_read_b64_tr_b16 v[224:225], v193 offset:0x2000
	ds_read_b64_tr_b16 v[226:227], v193 offset:0x2800
	ds_read_b64_tr_b16 v[232:233], v193 offset:0x3000
	ds_read_b64_tr_b16 v[234:235], v193 offset:0x3800
	s_waitcnt lgkmcnt(9)
	v_mfma_f32_32x32x16_bf16 v[80:95], v[236:239], v[96:99], v[80:95]
	v_permlane32_swap_b32_e32 v162, v164
	v_cvt_pk_bf16_f32 v166, v166, v173
	v_cvt_pk_bf16_f32 v167, v167, v172
	v_cvt_pk_bf16_f32 v168, v168, v171
	v_cvt_pk_bf16_f32 v169, v169, v170
	s_waitcnt lgkmcnt(8)
	v_mfma_f32_32x32x16_bf16 v[64:79], v[240:243], v[96:99], v[64:79]
	v_cvt_pk_bf16_f32 v170, v158, v159
	v_cvt_pk_bf16_f32 v171, v156, v157
	v_cvt_pk_bf16_f32 v172, v150, v151
	v_cvt_pk_bf16_f32 v173, v148, v149
	v_cvt_pk_bf16_f32 v212, v146, v147
	s_waitcnt vmcnt(0)
	ds_write_b128 v198, v[136:139] offset:32768
	ds_write_b128 v199, v[140:143] offset:32768
	s_sub_i32 s7, s8, 64
	s_cmp_lt_u32 s6, 2
	s_cselect_b32 s6, s15, s7
	s_ashr_i32 s7, s6, 31
	v_permlane32_swap_b32_e32 v163, v165
	s_waitcnt lgkmcnt(8)
	s_nop 0
	v_mfma_f32_32x32x16_bf16 v[48:63], v[162:165], v[216:219], v[48:63]
	ds_read_b64_tr_b16 v[216:217], v193 offset:0x200
	ds_read_b64_tr_b16 v[218:219], v193 offset:0xa00
	v_cvt_pk_bf16_f32 v213, v160, v161
	v_cvt_pk_bf16_f32 v214, v154, v155
	v_cvt_pk_bf16_f32 v215, v152, v153
	v_permlane32_swap_b32_e32 v166, v168
	v_permlane32_swap_b32_e32 v167, v169
	s_waitcnt lgkmcnt(8)
	s_nop 0
	v_mfma_f32_32x32x16_bf16 v[48:63], v[166:169], v[220:223], v[48:63]
	ds_read_b64_tr_b16 v[220:221], v193 offset:0x1200
	ds_read_b64_tr_b16 v[222:223], v193 offset:0x1a00
	v_permlane32_swap_b32_e32 v170, v172
	v_permlane32_swap_b32_e32 v171, v173
	v_permlane32_swap_b32_e32 v212, v214
	v_permlane32_swap_b32_e32 v213, v215
	v_lshl_add_u64 v[146:147], s[6:7], 0, v[178:179]
	s_waitcnt lgkmcnt(8)
	v_mfma_f32_32x32x16_bf16 v[48:63], v[170:173], v[224:227], v[48:63]
	ds_read_b64_tr_b16 v[224:225], v193 offset:0x2200
	ds_read_b64_tr_b16 v[226:227], v193 offset:0x2a00
	v_mul_lo_u32 v148, v147, s40
	v_mul_lo_u32 v149, v146, s41
	v_mad_u64_u32 v[146:147], s[10:11], v146, s40, 0
	v_add3_u32 v147, v147, v149, v148
	v_lshl_add_u64 v[148:149], v[180:181], 0, s[6:7]
	s_waitcnt lgkmcnt(8)
	v_mfma_f32_32x32x16_bf16 v[48:63], v[212:215], v[232:235], v[48:63]
	ds_read_b64_tr_b16 v[232:233], v193 offset:0x3200
	ds_read_b64_tr_b16 v[234:235], v193 offset:0x3a00
	v_mul_lo_u32 v150, v149, s40
	v_mul_lo_u32 v151, v148, s41
	v_mad_u64_u32 v[148:149], s[6:7], v148, s40, 0
	v_add3_u32 v149, v149, v151, v150
	v_lshlrev_b64 v[154:155], 1, v[146:147]
	s_waitcnt lgkmcnt(6)
	v_mfma_f32_32x32x16_bf16 v[32:47], v[162:165], v[216:219], v[32:47]
	ds_read_b64_tr_b16 v[216:217], v193 offset:0x400
	ds_read_b64_tr_b16 v[218:219], v193 offset:0xc00
	v_lshlrev_b64 v[156:157], 1, v[148:149]
	v_lshl_add_u64 v[146:147], v[182:183], 0, v[154:155]
	v_lshl_add_u64 v[150:151], v[182:183], 0, v[156:157]
	v_lshl_add_u64 v[154:155], v[184:185], 0, v[154:155]
	v_lshl_add_u64 v[158:159], v[184:185], 0, v[156:157]
	s_waitcnt lgkmcnt(6)
	v_mfma_f32_32x32x16_bf16 v[32:47], v[166:169], v[220:223], v[32:47]
	ds_read_b64_tr_b16 v[220:221], v193 offset:0x1400
	ds_read_b64_tr_b16 v[222:223], v193 offset:0x1c00
	v_max_f32_e32 v250, v81, v81
	v_max_f32_e32 v251, v80, v80
	v_max_f32_e32 v250, v251, v250
	v_max3_f32 v250, v250, v82, v83
	v_max3_f32 v250, v250, v84, v85
	global_load_dwordx4 v[146:149], v[146:147], off
	global_load_dwordx4 v[150:153], v[150:151], off
	global_load_dwordx4 v[154:157], v[154:155], off
	global_load_dwordx4 v[158:161], v[158:159], off
	s_waitcnt lgkmcnt(6)
	v_mfma_f32_32x32x16_bf16 v[32:47], v[170:173], v[224:227], v[32:47]
	ds_read_b64_tr_b16 v[224:225], v193 offset:0x2400
	ds_read_b64_tr_b16 v[226:227], v193 offset:0x2c00
	v_max3_f32 v250, v250, v86, v87
	v_max3_f32 v250, v250, v88, v89
	v_max3_f32 v250, v250, v90, v91
	v_max3_f32 v250, v250, v92, v93
	v_max3_f32 v250, v250, v94, v95
	s_waitcnt lgkmcnt(6)
	v_mfma_f32_32x32x16_bf16 v[32:47], v[212:215], v[232:235], v[32:47]
	ds_read_b64_tr_b16 v[232:233], v193 offset:0x3400
	ds_read_b64_tr_b16 v[234:235], v193 offset:0x3c00
	v_max3_f32 v250, v250, v64, v65
	v_max3_f32 v250, v250, v66, v67
	v_max3_f32 v250, v250, v68, v69
	v_max3_f32 v250, v250, v70, v71
	v_max3_f32 v250, v250, v72, v73
	s_waitcnt lgkmcnt(6)
	v_mfma_f32_32x32x16_bf16 v[16:31], v[162:165], v[216:219], v[16:31]
	ds_read_b64_tr_b16 v[216:217], v193 offset:0x600
	ds_read_b64_tr_b16 v[218:219], v193 offset:0xe00
	v_max3_f32 v250, v250, v74, v75
	v_max3_f32 v250, v250, v76, v77
	v_max3_f32 v250, v250, v78, v79
	v_mov_b32_e32 v251, v250
	s_nop 1
	v_permlane32_swap_b32_e32 v250, v251
	s_waitcnt lgkmcnt(6)
	v_mfma_f32_32x32x16_bf16 v[16:31], v[166:169], v[220:223], v[16:31]
	ds_read_b64_tr_b16 v[220:221], v193 offset:0x1600
	ds_read_b64_tr_b16 v[222:223], v193 offset:0x1e00
	v_max_f32_e32 v251, v251, v251
	v_max_f32_e32 v250, v250, v250
	v_max_f32_e32 v250, v250, v251
	v_sub_f32_e32 v251, v250, v174
	v_cmp_ge_f32_e32 vcc, s93, v251
	s_waitcnt lgkmcnt(6)
	v_mfma_f32_32x32x16_bf16 v[16:31], v[170:173], v[224:227], v[16:31]
	ds_read_b64_tr_b16 v[224:225], v193 offset:0x2600
	ds_read_b64_tr_b16 v[226:227], v193 offset:0x2e00
	v_max_f32_e32 v251, v174, v174
	v_max_f32_e32 v250, v251, v250
	v_sub_f32_e32 v251, v174, v250
	v_mul_f32_e32 v251, 0x3e0293ee, v251
	s_waitcnt lgkmcnt(6)
	v_mfma_f32_32x32x16_bf16 v[16:31], v[212:215], v[232:235], v[16:31]
	ds_read_b64_tr_b16 v[232:233], v193 offset:0x3600
	ds_read_b64_tr_b16 v[234:235], v193 offset:0x3e00
	v_exp_f32_e32 v251, v251
	s_waitcnt lgkmcnt(6)
	v_mfma_f32_32x32x16_bf16 v[0:15], v[162:165], v[216:219], v[0:15]
	s_waitcnt lgkmcnt(4)
	v_mfma_f32_32x32x16_bf16 v[0:15], v[166:169], v[220:223], v[0:15]
	s_waitcnt lgkmcnt(2)
	v_mfma_f32_32x32x16_bf16 v[0:15], v[170:173], v[224:227], v[0:15]
	s_waitcnt lgkmcnt(0)
	v_mfma_f32_32x32x16_bf16 v[0:15], v[212:215], v[232:235], v[0:15]
	s_cmp_eq_u64 vcc, exec
	s_cselect_b64 s[6:7], -1, 0
	s_barrier
	v_cndmask_b32_e64 v217, v251, 1.0, s[6:7]
	v_cmp_gt_f32_e32 vcc, 1.0, v217
	ds_write_b128 v195, v[128:131]
	ds_write_b128 v196, v[132:135]
	s_cbranch_vccz .LBB0_743
	s_and_saveexec_b64 s[10:11], s[4:5]
	ds_write_b32 v194, v217 offset:128
	s_or_b64 exec, exec, s[10:11]
	s_waitcnt lgkmcnt(0)
	v_add_u32_e32 v163, v192, v144
	ds_read_b128 v[164:167], v163 offset:224
	ds_read_b128 v[168:171], v163 offset:192
	ds_read_b128 v[212:215], v163 offset:160
	ds_read_b128 v[218:221], v163 offset:128
	s_waitcnt lgkmcnt(3)
	v_pk_mul_f32 v[60:61], v[60:61], v[164:165]
	s_waitcnt lgkmcnt(2)
	v_pk_mul_f32 v[56:57], v[56:57], v[168:169]
	s_waitcnt lgkmcnt(1)
	v_pk_mul_f32 v[52:53], v[52:53], v[212:213]
	v_pk_mul_f32 v[62:63], v[62:63], v[166:167]
	v_pk_mul_f32 v[58:59], v[58:59], v[170:171]
	v_pk_mul_f32 v[54:55], v[54:55], v[214:215]
	s_waitcnt lgkmcnt(0)
	v_pk_mul_f32 v[50:51], v[50:51], v[220:221]
	v_pk_mul_f32 v[48:49], v[48:49], v[218:219]
	v_pk_mul_f32 v[44:45], v[44:45], v[164:165]
	v_pk_mul_f32 v[40:41], v[40:41], v[168:169]
	v_pk_mul_f32 v[36:37], v[36:37], v[212:213]
	v_pk_mul_f32 v[46:47], v[46:47], v[166:167]
	v_pk_mul_f32 v[42:43], v[42:43], v[170:171]
	v_pk_mul_f32 v[38:39], v[38:39], v[214:215]
	v_pk_mul_f32 v[34:35], v[34:35], v[220:221]
	v_pk_mul_f32 v[32:33], v[32:33], v[218:219]
	v_pk_mul_f32 v[28:29], v[28:29], v[164:165]
	v_pk_mul_f32 v[24:25], v[24:25], v[168:169]
	v_pk_mul_f32 v[20:21], v[20:21], v[212:213]
	v_pk_mul_f32 v[30:31], v[30:31], v[166:167]
	v_pk_mul_f32 v[26:27], v[26:27], v[170:171]
	v_pk_mul_f32 v[22:23], v[22:23], v[214:215]
	v_pk_mul_f32 v[18:19], v[18:19], v[220:221]
	v_pk_mul_f32 v[16:17], v[16:17], v[218:219]
	v_pk_mul_f32 v[12:13], v[12:13], v[164:165]
	v_pk_mul_f32 v[8:9], v[8:9], v[168:169]
	v_pk_mul_f32 v[4:5], v[4:5], v[212:213]
	v_pk_mul_f32 v[14:15], v[14:15], v[166:167]
	v_pk_mul_f32 v[10:11], v[10:11], v[170:171]
	v_pk_mul_f32 v[6:7], v[6:7], v[214:215]
	v_pk_mul_f32 v[2:3], v[2:3], v[220:221]
	v_pk_mul_f32 v[0:1], v[0:1], v[218:219]
.LBB0_743:
	v_cndmask_b32_e64 v216, v250, v174, s[6:7]
	v_mul_f32_e32 v212, 0xbe0293ee, v216
	v_fmamk_f32 v80, v80, 0x3e0293ee, v212
	v_fmamk_f32 v81, v81, 0x3e0293ee, v212
	v_fmamk_f32 v82, v82, 0x3e0293ee, v212
	v_fmamk_f32 v83, v83, 0x3e0293ee, v212
	v_fmamk_f32 v84, v84, 0x3e0293ee, v212
	v_fmamk_f32 v85, v85, 0x3e0293ee, v212
	v_fmamk_f32 v86, v86, 0x3e0293ee, v212
	v_fmamk_f32 v87, v87, 0x3e0293ee, v212
	v_fmamk_f32 v88, v88, 0x3e0293ee, v212
	v_fmamk_f32 v89, v89, 0x3e0293ee, v212
	v_fmamk_f32 v90, v90, 0x3e0293ee, v212
	v_fmamk_f32 v91, v91, 0x3e0293ee, v212
	v_fmamk_f32 v92, v92, 0x3e0293ee, v212
	v_fmamk_f32 v93, v93, 0x3e0293ee, v212
	v_fmamk_f32 v94, v94, 0x3e0293ee, v212
	v_fmamk_f32 v95, v95, 0x3e0293ee, v212
	v_exp_f32_e32 v162, v80
	v_exp_f32_e32 v177, v81
	v_exp_f32_e32 v163, v82
	v_exp_f32_e32 v176, v83
	v_exp_f32_e32 v164, v84
	v_exp_f32_e32 v175, v85
	v_exp_f32_e32 v165, v86
	v_exp_f32_e32 v174, v87
	v_exp_f32_e32 v166, v88
	v_exp_f32_e32 v173, v89
	v_exp_f32_e32 v167, v90
	v_exp_f32_e32 v172, v91
	v_exp_f32_e32 v168, v92
	v_exp_f32_e32 v171, v93
	v_exp_f32_e32 v169, v94
	v_exp_f32_e32 v170, v95
	v_fmamk_f32 v219, v70, 0x3e0293ee, v212
	v_fmamk_f32 v220, v71, 0x3e0293ee, v212
	v_fmamk_f32 v225, v64, 0x3e0293ee, v212
	v_fmamk_f32 v226, v65, 0x3e0293ee, v212
	v_fmamk_f32 v227, v66, 0x3e0293ee, v212
	v_fmamk_f32 v232, v67, 0x3e0293ee, v212
	v_fmamk_f32 v233, v68, 0x3e0293ee, v212
	v_fmamk_f32 v218, v69, 0x3e0293ee, v212
	v_fmamk_f32 v221, v72, 0x3e0293ee, v212
	v_fmamk_f32 v222, v73, 0x3e0293ee, v212
	v_fmamk_f32 v223, v74, 0x3e0293ee, v212
	v_fmamk_f32 v224, v75, 0x3e0293ee, v212
	v_fmamk_f32 v213, v76, 0x3e0293ee, v212
	v_fmamk_f32 v234, v77, 0x3e0293ee, v212
	v_fmamk_f32 v235, v78, 0x3e0293ee, v212
	v_fmac_f32_e32 v212, 0x3e0293ee, v79
	ds_read_b128 v[64:67], v200 offset:32768
	ds_read_b128 v[68:71], v200 offset:40960
	ds_read_b128 v[240:243], v208 offset:32768
	ds_read_b128 v[244:247], v208 offset:40960
	ds_read_b128 v[248:251], v207 offset:32768
	s_waitcnt lgkmcnt(4)
	v_mfma_f32_32x32x16_bf16 v[80:95], v[64:67], v[124:127], 0
	v_exp_f32_e32 v215, v226
	v_exp_f32_e32 v226, v232
	s_waitcnt lgkmcnt(3)
	v_mfma_f32_32x32x16_bf16 v[64:79], v[68:71], v[124:127], 0
	v_exp_f32_e32 v232, v219
	v_add_f32_e32 v219, 0, v162
	v_add_f32_e32 v219, v177, v219
	v_add_f32_e32 v219, v163, v219
	s_waitcnt lgkmcnt(2)
	v_mfma_f32_32x32x16_bf16 v[80:95], v[240:243], v[120:123], v[80:95]
	ds_read_b128 v[240:243], v207 offset:40960
	v_add_f32_e32 v219, v176, v219
	v_add_f32_e32 v219, v164, v219
	v_add_f32_e32 v219, v175, v219
	v_add_f32_e32 v219, v165, v219
	v_add_f32_e32 v219, v174, v219
	s_waitcnt lgkmcnt(2)
	v_mfma_f32_32x32x16_bf16 v[64:79], v[244:247], v[120:123], v[64:79]
	ds_read_b128 v[244:247], v206 offset:32768
	v_add_f32_e32 v219, v166, v219
	v_add_f32_e32 v219, v173, v219
	v_add_f32_e32 v219, v167, v219
	v_add_f32_e32 v219, v172, v219
	v_add_f32_e32 v219, v168, v219
	s_waitcnt lgkmcnt(2)
	v_mfma_f32_32x32x16_bf16 v[80:95], v[248:251], v[116:119], v[80:95]
	ds_read_b128 v[248:251], v206 offset:40960
	v_exp_f32_e32 v214, v225
	v_add_f32_e32 v219, v171, v219
	v_exp_f32_e32 v225, v227
	s_waitcnt lgkmcnt(2)
	v_mfma_f32_32x32x16_bf16 v[64:79], v[240:243], v[116:119], v[64:79]
	ds_read_b128 v[240:243], v205 offset:32768
	v_add_f32_e32 v219, v169, v219
	v_add_f32_e32 v219, v170, v219
	v_exp_f32_e32 v227, v233
	v_add_f32_e32 v219, v214, v219
	s_waitcnt lgkmcnt(2)
	v_mfma_f32_32x32x16_bf16 v[80:95], v[244:247], v[112:115], v[80:95]
	ds_read_b128 v[244:247], v205 offset:40960
	v_exp_f32_e32 v218, v218
	v_add_f32_e32 v219, v215, v219
	v_add_f32_e32 v219, v225, v219
	v_add_f32_e32 v219, v226, v219
	s_waitcnt lgkmcnt(2)
	v_mfma_f32_32x32x16_bf16 v[64:79], v[248:251], v[112:115], v[64:79]
	ds_read_b128 v[248:251], v204 offset:32768
	v_exp_f32_e32 v233, v220
	v_exp_f32_e32 v221, v221
	v_add_f32_e32 v219, v227, v219
	s_waitcnt lgkmcnt(2)
	v_mfma_f32_32x32x16_bf16 v[80:95], v[240:243], v[108:111], v[80:95]
	ds_read_b128 v[240:243], v204 offset:40960
	v_exp_f32_e32 v222, v222
	v_add_f32_e32 v219, v218, v219
	v_exp_f32_e32 v223, v223
	s_waitcnt lgkmcnt(2)
	v_mfma_f32_32x32x16_bf16 v[64:79], v[244:247], v[108:111], v[64:79]
	ds_read_b128 v[244:247], v202 offset:32768
	v_add_f32_e32 v219, v232, v219
	v_exp_f32_e32 v224, v224
	v_add_f32_e32 v219, v233, v219
	v_add_f32_e32 v219, v221, v219
	s_waitcnt lgkmcnt(2)
	v_mfma_f32_32x32x16_bf16 v[80:95], v[248:251], v[104:107], v[80:95]
	ds_read_b128 v[248:251], v202 offset:40960
	v_exp_f32_e32 v213, v213
	v_exp_f32_e32 v234, v234
	v_add_f32_e32 v219, v222, v219
	s_waitcnt lgkmcnt(2)
	v_mfma_f32_32x32x16_bf16 v[64:79], v[240:243], v[104:107], v[64:79]
	ds_read_b128 v[240:243], v201 offset:32768
	v_exp_f32_e32 v235, v235
	v_add_f32_e32 v219, v223, v219
	v_exp_f32_e32 v212, v212
	s_waitcnt lgkmcnt(2)
	v_mfma_f32_32x32x16_bf16 v[80:95], v[244:247], v[100:103], v[80:95]
	ds_read_b128 v[244:247], v201 offset:40960
	v_add_f32_e32 v219, v224, v219
	v_add_f32_e32 v219, v213, v219
	v_add_f32_e32 v219, v234, v219
	v_add_f32_e32 v219, v235, v219
	v_add_f32_e32 v219, v212, v219
	s_waitcnt lgkmcnt(2)
	v_mfma_f32_32x32x16_bf16 v[64:79], v[248:251], v[100:103], v[64:79]
	v_mov_b32_e32 v220, v219
	s_nop 1
	v_permlane32_swap_b32_e32 v219, v220
	v_cvt_pk_bf16_f32 v162, v162, v177
	v_cvt_pk_bf16_f32 v163, v163, v176
	v_cvt_pk_bf16_f32 v164, v164, v175
	s_waitcnt lgkmcnt(1)
	v_mfma_f32_32x32x16_bf16 v[80:95], v[240:243], v[96:99], v[80:95]
	v_cvt_pk_bf16_f32 v165, v165, v174
	v_cvt_pk_bf16_f32 v166, v166, v173
	v_cvt_pk_bf16_f32 v167, v167, v172
	v_cvt_pk_bf16_f32 v168, v168, v171
	v_cvt_pk_bf16_f32 v169, v169, v170
	s_waitcnt lgkmcnt(0)
	v_mfma_f32_32x32x16_bf16 v[64:79], v[244:247], v[96:99], v[64:79]
	v_cvt_pk_bf16_f32 v170, v214, v215
	v_cvt_pk_bf16_f32 v171, v225, v226
	v_cvt_pk_bf16_f32 v172, v227, v218
	v_cvt_pk_bf16_f32 v173, v232, v233
	v_cvt_pk_bf16_f32 v174, v221, v222
	s_cmp_ge_u32 s14, s91
	s_cselect_b64 s[10:11], -1, 0
	s_waitcnt vmcnt(0)
	ds_write_b128 v198, v[154:157] offset:49152
	ds_write_b128 v199, v[158:161] offset:49152
	s_ashr_i32 s9, s8, 31
	v_cvt_pk_bf16_f32 v176, v213, v234
	v_cvt_pk_bf16_f32 v177, v235, v212
	v_permlane32_swap_b32_e32 v162, v164
	v_permlane32_swap_b32_e32 v163, v165
	ds_read_b64_tr_b16 v[212:213], v197 offset:0
	ds_read_b64_tr_b16 v[214:215], v197 offset:0x800
	s_waitcnt lgkmcnt(0)
	v_mfma_f32_32x32x16_bf16 v[48:63], v[162:165], v[212:215], v[48:63]
	v_cvt_pk_bf16_f32 v175, v223, v224
	v_permlane32_swap_b32_e32 v166, v168
	v_permlane32_swap_b32_e32 v167, v169
	v_permlane32_swap_b32_e32 v170, v172
	v_permlane32_swap_b32_e32 v171, v173
	ds_read_b64_tr_b16 v[222:223], v197 offset:0x1000
	ds_read_b64_tr_b16 v[224:225], v197 offset:0x1800
	ds_read_b64_tr_b16 v[232:233], v197 offset:0x2000
	ds_read_b64_tr_b16 v[234:235], v197 offset:0x2800
	ds_read_b64_tr_b16 v[236:237], v197 offset:0x3000
	ds_read_b64_tr_b16 v[238:239], v197 offset:0x3800
	ds_read_b64_tr_b16 v[212:213], v197 offset:0x200
	ds_read_b64_tr_b16 v[214:215], v197 offset:0xa00
	s_waitcnt lgkmcnt(6)
	v_mfma_f32_32x32x16_bf16 v[48:63], v[166:169], v[222:225], v[48:63]
	ds_read_b64_tr_b16 v[222:223], v197 offset:0x1200
	ds_read_b64_tr_b16 v[224:225], v197 offset:0x1a00
	v_permlane32_swap_b32_e32 v174, v176
	v_permlane32_swap_b32_e32 v175, v177
	v_lshl_add_u64 v[128:129], s[8:9], 0, v[178:179]
	v_mul_lo_u32 v130, v129, s40
	v_mul_lo_u32 v131, v128, s41
	s_waitcnt lgkmcnt(6)
	v_mfma_f32_32x32x16_bf16 v[48:63], v[170:173], v[232:235], v[48:63]
	ds_read_b64_tr_b16 v[232:233], v197 offset:0x2200
	ds_read_b64_tr_b16 v[234:235], v197 offset:0x2a00
	v_mad_u64_u32 v[128:129], s[6:7], v128, s40, 0
	v_add3_u32 v129, v129, v131, v130
	v_lshl_add_u64 v[130:131], v[180:181], 0, s[8:9]
	v_mul_lo_u32 v132, v131, s40
	v_mul_lo_u32 v133, v130, s41
	s_waitcnt lgkmcnt(6)
	v_mfma_f32_32x32x16_bf16 v[48:63], v[174:177], v[236:239], v[48:63]
	ds_read_b64_tr_b16 v[236:237], v197 offset:0x3200
	ds_read_b64_tr_b16 v[238:239], v197 offset:0x3a00
	v_mad_u64_u32 v[130:131], s[6:7], v130, s40, 0
	v_add3_u32 v131, v131, v133, v132
	v_lshlrev_b64 v[136:137], 1, v[128:129]
	v_lshlrev_b64 v[138:139], 1, v[130:131]
	v_lshl_add_u64 v[128:129], v[182:183], 0, v[136:137]
	s_waitcnt lgkmcnt(6)
	v_mfma_f32_32x32x16_bf16 v[32:47], v[162:165], v[212:215], v[32:47]
	ds_read_b64_tr_b16 v[212:213], v197 offset:0x400
	ds_read_b64_tr_b16 v[214:215], v197 offset:0xc00
	v_lshl_add_u64 v[132:133], v[182:183], 0, v[138:139]
	v_lshl_add_u64 v[136:137], v[184:185], 0, v[136:137]
	v_lshl_add_u64 v[140:141], v[184:185], 0, v[138:139]
	v_max_f32_e32 v250, v81, v81
	v_max_f32_e32 v251, v80, v80
	s_waitcnt lgkmcnt(6)
	v_mfma_f32_32x32x16_bf16 v[32:47], v[166:169], v[222:225], v[32:47]
	ds_read_b64_tr_b16 v[222:223], v197 offset:0x1400
	ds_read_b64_tr_b16 v[224:225], v197 offset:0x1c00
	v_max_f32_e32 v250, v251, v250
	v_max3_f32 v250, v250, v82, v83
	v_max3_f32 v250, v250, v84, v85
	v_max3_f32 v250, v250, v86, v87
	v_max3_f32 v250, v250, v88, v89
	global_load_dwordx4 v[128:131], v[128:129], off
	global_load_dwordx4 v[132:135], v[132:133], off
	global_load_dwordx4 v[136:139], v[136:137], off
	global_load_dwordx4 v[140:143], v[140:141], off
	s_waitcnt lgkmcnt(6)
	v_mfma_f32_32x32x16_bf16 v[32:47], v[170:173], v[232:235], v[32:47]
	ds_read_b64_tr_b16 v[232:233], v197 offset:0x2400
	ds_read_b64_tr_b16 v[234:235], v197 offset:0x2c00
	v_max3_f32 v250, v250, v90, v91
	v_max3_f32 v250, v250, v92, v93
	v_max3_f32 v250, v250, v94, v95
	v_max3_f32 v250, v250, v64, v65
	v_max3_f32 v250, v250, v66, v67
	s_waitcnt lgkmcnt(6)
	v_mfma_f32_32x32x16_bf16 v[32:47], v[174:177], v[236:239], v[32:47]
	ds_read_b64_tr_b16 v[236:237], v197 offset:0x3400
	ds_read_b64_tr_b16 v[238:239], v197 offset:0x3c00
	v_max3_f32 v250, v250, v68, v69
	v_max3_f32 v250, v250, v70, v71
	v_max3_f32 v250, v250, v72, v73
	v_max3_f32 v250, v250, v74, v75
	v_max3_f32 v250, v250, v76, v77
	s_waitcnt lgkmcnt(6)
	v_mfma_f32_32x32x16_bf16 v[16:31], v[162:165], v[212:215], v[16:31]
	ds_read_b64_tr_b16 v[212:213], v197 offset:0x600
	ds_read_b64_tr_b16 v[214:215], v197 offset:0xe00
	v_max3_f32 v250, v250, v78, v79
	v_mov_b32_e32 v251, v250
	s_nop 1
	v_permlane32_swap_b32_e32 v250, v251
	v_max_f32_e32 v251, v251, v251
	v_max_f32_e32 v250, v250, v250
	s_waitcnt lgkmcnt(6)
	v_mfma_f32_32x32x16_bf16 v[16:31], v[166:169], v[222:225], v[16:31]
	ds_read_b64_tr_b16 v[222:223], v197 offset:0x1600
	ds_read_b64_tr_b16 v[224:225], v197 offset:0x1e00
	v_max_f32_e32 v250, v250, v251
	v_sub_f32_e32 v251, v250, v216
	v_cmp_ge_f32_e32 vcc, s93, v251
	v_max_f32_e32 v251, v216, v216
	v_max_f32_e32 v250, v251, v250
	s_waitcnt lgkmcnt(6)
	v_mfma_f32_32x32x16_bf16 v[16:31], v[170:173], v[232:235], v[16:31]
	ds_read_b64_tr_b16 v[232:233], v197 offset:0x2600
	ds_read_b64_tr_b16 v[234:235], v197 offset:0x2e00
	v_sub_f32_e32 v251, v216, v250
	v_mul_f32_e32 v251, 0x3e0293ee, v251
	v_exp_f32_e32 v251, v251
	s_waitcnt lgkmcnt(6)
	v_mfma_f32_32x32x16_bf16 v[16:31], v[174:177], v[236:239], v[16:31]
	ds_read_b64_tr_b16 v[236:237], v197 offset:0x3600
	ds_read_b64_tr_b16 v[238:239], v197 offset:0x3e00
	s_waitcnt lgkmcnt(6)
	v_mfma_f32_32x32x16_bf16 v[0:15], v[162:165], v[212:215], v[0:15]
	s_waitcnt lgkmcnt(4)
	v_mfma_f32_32x32x16_bf16 v[0:15], v[166:169], v[222:225], v[0:15]
	s_waitcnt lgkmcnt(2)
	v_mfma_f32_32x32x16_bf16 v[0:15], v[170:173], v[232:235], v[0:15]
	s_waitcnt lgkmcnt(0)
	v_mfma_f32_32x32x16_bf16 v[0:15], v[174:177], v[236:239], v[0:15]
	s_cmp_eq_u64 vcc, exec
	s_cselect_b64 s[6:7], -1, 0
	s_barrier
	v_cndmask_b32_e64 v218, v251, 1.0, s[6:7]
	v_cmp_gt_f32_e32 vcc, 1.0, v218
	ds_write_b128 v195, v[146:149] offset:16384
	ds_write_b128 v196, v[150:153] offset:16384
	s_cbranch_vccz .LBB0_749
	s_and_saveexec_b64 s[12:13], s[4:5]
	ds_write_b32 v194, v218 offset:128
	s_or_b64 exec, exec, s[12:13]
	s_waitcnt lgkmcnt(0)
	v_add_u32_e32 v158, v192, v144
	ds_read_b128 v[146:149], v158 offset:224
	ds_read_b128 v[150:153], v158 offset:192
	ds_read_b128 v[154:157], v158 offset:160
	ds_read_b128 v[158:161], v158 offset:128
	s_waitcnt lgkmcnt(3)
	v_pk_mul_f32 v[60:61], v[60:61], v[146:147]
	s_waitcnt lgkmcnt(2)
	v_pk_mul_f32 v[56:57], v[56:57], v[150:151]
	s_waitcnt lgkmcnt(1)
	v_pk_mul_f32 v[52:53], v[52:53], v[154:155]
	v_pk_mul_f32 v[62:63], v[62:63], v[148:149]
	v_pk_mul_f32 v[58:59], v[58:59], v[152:153]
	v_pk_mul_f32 v[54:55], v[54:55], v[156:157]
	s_waitcnt lgkmcnt(0)
	v_pk_mul_f32 v[50:51], v[50:51], v[160:161]
	v_pk_mul_f32 v[48:49], v[48:49], v[158:159]
	v_pk_mul_f32 v[44:45], v[44:45], v[146:147]
	v_pk_mul_f32 v[40:41], v[40:41], v[150:151]
	v_pk_mul_f32 v[36:37], v[36:37], v[154:155]
	v_pk_mul_f32 v[46:47], v[46:47], v[148:149]
	v_pk_mul_f32 v[42:43], v[42:43], v[152:153]
	v_pk_mul_f32 v[38:39], v[38:39], v[156:157]
	v_pk_mul_f32 v[34:35], v[34:35], v[160:161]
	v_pk_mul_f32 v[32:33], v[32:33], v[158:159]
	v_pk_mul_f32 v[28:29], v[28:29], v[146:147]
	v_pk_mul_f32 v[24:25], v[24:25], v[150:151]
	v_pk_mul_f32 v[20:21], v[20:21], v[154:155]
	v_pk_mul_f32 v[30:31], v[30:31], v[148:149]
	v_pk_mul_f32 v[26:27], v[26:27], v[152:153]
	v_pk_mul_f32 v[22:23], v[22:23], v[156:157]
	v_pk_mul_f32 v[18:19], v[18:19], v[160:161]
	v_pk_mul_f32 v[16:17], v[16:17], v[158:159]
	v_pk_mul_f32 v[12:13], v[12:13], v[146:147]
	v_pk_mul_f32 v[8:9], v[8:9], v[150:151]
	v_pk_mul_f32 v[4:5], v[4:5], v[154:155]
	v_pk_mul_f32 v[14:15], v[14:15], v[148:149]
	v_pk_mul_f32 v[10:11], v[10:11], v[152:153]
	v_pk_mul_f32 v[6:7], v[6:7], v[156:157]
	v_pk_mul_f32 v[2:3], v[2:3], v[160:161]
	v_pk_mul_f32 v[0:1], v[0:1], v[158:159]
.LBB0_749:
	v_cndmask_b32_e64 v174, v250, v216, s[6:7]
	v_mul_f32_e32 v152, 0xbe0293ee, v174
	v_mov_b32_e32 v153, v152
	v_fmamk_f32 v80, v80, 0x3e0293ee, v152
	v_fmamk_f32 v81, v81, 0x3e0293ee, v152
	v_fmamk_f32 v82, v82, 0x3e0293ee, v152
	v_fmamk_f32 v83, v83, 0x3e0293ee, v152
	v_fmamk_f32 v84, v84, 0x3e0293ee, v152
	v_fmamk_f32 v85, v85, 0x3e0293ee, v152
	v_fmamk_f32 v86, v86, 0x3e0293ee, v152
	v_fmamk_f32 v87, v87, 0x3e0293ee, v152
	v_fmamk_f32 v88, v88, 0x3e0293ee, v152
	v_fmamk_f32 v89, v89, 0x3e0293ee, v152
	v_fmamk_f32 v90, v90, 0x3e0293ee, v152
	v_fmamk_f32 v91, v91, 0x3e0293ee, v152
	v_fmamk_f32 v92, v92, 0x3e0293ee, v152
	v_fmamk_f32 v93, v93, 0x3e0293ee, v152
	v_fmamk_f32 v94, v94, 0x3e0293ee, v152
	v_fmac_f32_e32 v153, 0x3e0293ee, v95
	v_exp_f32_e32 v162, v80
	v_exp_f32_e32 v216, v81
	v_exp_f32_e32 v163, v82
	v_exp_f32_e32 v177, v83
	v_exp_f32_e32 v164, v84
	v_exp_f32_e32 v176, v85
	v_exp_f32_e32 v165, v86
	v_exp_f32_e32 v175, v87
	v_exp_f32_e32 v166, v88
	v_exp_f32_e32 v173, v89
	v_exp_f32_e32 v167, v90
	v_exp_f32_e32 v172, v91
	v_exp_f32_e32 v168, v92
	v_exp_f32_e32 v171, v93
	v_exp_f32_e32 v169, v94
	v_exp_f32_e32 v170, v153
	v_pk_fma_f32 v[158:159], v[64:65], s[92:93], v[152:153] op_sel_hi:[1,0,0]
	v_add_f32_e32 v64, v210, v211
	v_fmac_f32_e32 v64, v209, v203
	v_add_f32_e32 v203, v219, v220
	v_pk_fma_f32 v[156:157], v[66:67], s[92:93], v[152:153] op_sel_hi:[1,0,0]
	v_pk_fma_f32 v[150:151], v[68:69], s[92:93], v[152:153] op_sel_hi:[1,0,0]
	v_pk_fma_f32 v[148:149], v[70:71], s[92:93], v[152:153] op_sel_hi:[1,0,0]
	v_pk_fma_f32 v[146:147], v[72:73], s[92:93], v[152:153] op_sel_hi:[1,0,0]
	v_pk_fma_f32 v[160:161], v[74:75], s[92:93], v[152:153] op_sel_hi:[1,0,0]
	v_pk_fma_f32 v[154:155], v[76:77], s[92:93], v[152:153] op_sel_hi:[1,0,0]
	v_pk_fma_f32 v[152:153], v[78:79], s[92:93], v[152:153] op_sel_hi:[1,0,0]
	v_fmac_f32_e32 v203, v64, v217
	s_add_i32 s14, s14, 2
	s_addk_i32 s8, 0x80
	s_addk_i32 s15, 0x80
	s_and_b64 vcc, exec, s[10:11]
	s_cbranch_vccnz .LBB0_751
	v_mov_b32_e32 v209, v218
	s_branch .LBB0_739
.LBB0_751:
	s_waitcnt vmcnt(0)
	ds_read_b128 v[64:67], v200 offset:49152
	ds_read_b128 v[68:71], v200 offset:57344
	s_waitcnt lgkmcnt(1)
	v_mfma_f32_32x32x16_bf16 v[80:95], v[64:67], v[124:127], 0
	s_waitcnt lgkmcnt(0)
	v_mfma_f32_32x32x16_bf16 v[64:79], v[68:71], v[124:127], 0
	ds_read_b128 v[124:127], v208 offset:49152
	ds_read_b128 v[128:131], v208 offset:57344
	s_waitcnt lgkmcnt(1)
	v_mfma_f32_32x32x16_bf16 v[80:95], v[124:127], v[120:123], v[80:95]
	s_waitcnt lgkmcnt(0)
	v_mfma_f32_32x32x16_bf16 v[64:79], v[128:131], v[120:123], v[64:79]
	ds_read_b128 v[120:123], v207 offset:49152
	ds_read_b128 v[124:127], v207 offset:57344
	s_waitcnt lgkmcnt(1)
	v_mfma_f32_32x32x16_bf16 v[80:95], v[120:123], v[116:119], v[80:95]
	s_waitcnt lgkmcnt(0)
	v_mfma_f32_32x32x16_bf16 v[64:79], v[124:127], v[116:119], v[64:79]
	ds_read_b128 v[116:119], v206 offset:49152
	ds_read_b128 v[120:123], v206 offset:57344
	s_waitcnt lgkmcnt(1)
	v_mfma_f32_32x32x16_bf16 v[80:95], v[116:119], v[112:115], v[80:95]
	s_waitcnt lgkmcnt(0)
	v_mfma_f32_32x32x16_bf16 v[64:79], v[120:123], v[112:115], v[64:79]
	ds_read_b128 v[112:115], v205 offset:49152
	ds_read_b128 v[116:119], v205 offset:57344
	v_exp_f32_e32 v120, v152
	v_exp_f32_e32 v121, v153
	s_waitcnt lgkmcnt(1)
	v_mfma_f32_32x32x16_bf16 v[80:95], v[112:115], v[108:111], v[80:95]
	s_waitcnt lgkmcnt(0)
	v_mfma_f32_32x32x16_bf16 v[64:79], v[116:119], v[108:111], v[64:79]
	ds_read_b128 v[108:111], v204 offset:49152
	ds_read_b128 v[112:115], v204 offset:57344
	v_exp_f32_e32 v116, v160
	v_exp_f32_e32 v117, v161
	v_exp_f32_e32 v118, v154
	v_exp_f32_e32 v119, v155
	s_waitcnt lgkmcnt(1)
	v_mfma_f32_32x32x16_bf16 v[80:95], v[108:111], v[104:107], v[80:95]
	s_waitcnt lgkmcnt(0)
	v_mfma_f32_32x32x16_bf16 v[64:79], v[112:115], v[104:107], v[64:79]
	ds_read_b128 v[104:107], v202 offset:49152
	ds_read_b128 v[108:111], v202 offset:57344
	v_exp_f32_e32 v112, v148
	v_exp_f32_e32 v113, v149
	v_exp_f32_e32 v114, v146
	v_exp_f32_e32 v115, v147
	s_waitcnt lgkmcnt(1)
	v_mfma_f32_32x32x16_bf16 v[80:95], v[104:107], v[100:103], v[80:95]
	s_waitcnt lgkmcnt(0)
	v_mfma_f32_32x32x16_bf16 v[64:79], v[108:111], v[100:103], v[64:79]
	ds_read_b128 v[100:103], v201 offset:49152
	ds_read_b128 v[104:107], v201 offset:57344
	v_exp_f32_e32 v108, v156
	v_exp_f32_e32 v109, v157
	v_exp_f32_e32 v110, v150
	v_exp_f32_e32 v111, v151
	s_waitcnt lgkmcnt(1)
	v_mfma_f32_32x32x16_bf16 v[80:95], v[100:103], v[96:99], v[80:95]
	s_waitcnt lgkmcnt(0)
	v_mfma_f32_32x32x16_bf16 v[64:79], v[104:107], v[96:99], v[64:79]
	v_add_f32_e32 v96, 0, v162
	v_add_f32_e32 v96, v216, v96
	v_add_f32_e32 v96, v163, v96
	v_add_f32_e32 v96, v177, v96
	v_add_f32_e32 v96, v164, v96
	v_add_f32_e32 v96, v176, v96
	v_add_f32_e32 v96, v165, v96
	v_add_f32_e32 v96, v175, v96
	v_add_f32_e32 v96, v166, v96
	v_add_f32_e32 v96, v173, v96
	v_add_f32_e32 v96, v167, v96
	v_add_f32_e32 v96, v172, v96
	v_exp_f32_e32 v106, v158
	v_add_f32_e32 v96, v168, v96
	v_exp_f32_e32 v107, v159
	v_add_f32_e32 v96, v171, v96
	v_add_f32_e32 v96, v169, v96
	v_add_f32_e32 v96, v170, v96
	v_add_f32_e32 v96, v106, v96
	v_add_f32_e32 v96, v107, v96
	v_add_f32_e32 v96, v108, v96
	v_add_f32_e32 v96, v109, v96
	v_add_f32_e32 v96, v110, v96
	v_add_f32_e32 v96, v111, v96
	v_add_f32_e32 v96, v112, v96
	v_add_f32_e32 v96, v113, v96
	v_add_f32_e32 v96, v114, v96
	v_add_f32_e32 v96, v115, v96
	v_add_f32_e32 v96, v116, v96
	v_add_f32_e32 v96, v117, v96
	v_add_f32_e32 v96, v118, v96
	v_add_f32_e32 v96, v119, v96
	v_add_f32_e32 v96, v120, v96
	v_add_f32_e32 v100, v121, v96
	v_mov_b32_e32 v101, v100
	v_cvt_pk_bf16_f32 v96, v162, v216
	v_cvt_pk_bf16_f32 v97, v163, v177
	v_cvt_pk_bf16_f32 v98, v164, v176
	v_cvt_pk_bf16_f32 v99, v165, v175
	s_nop 1
	v_permlane32_swap_b32_e32 v100, v101
	v_permlane32_swap_b32_e32 v96, v98
	v_permlane32_swap_b32_e32 v97, v99
	v_cvt_pk_bf16_f32 v102, v166, v173
	v_cvt_pk_bf16_f32 v103, v167, v172
	v_cvt_pk_bf16_f32 v104, v168, v171
	v_cvt_pk_bf16_f32 v105, v169, v170
	v_cvt_pk_bf16_f32 v106, v106, v107
	v_cvt_pk_bf16_f32 v107, v108, v109
	v_cvt_pk_bf16_f32 v108, v110, v111
	v_cvt_pk_bf16_f32 v109, v112, v113
	v_cvt_pk_bf16_f32 v110, v114, v115
	v_cvt_pk_bf16_f32 v111, v116, v117
	v_cvt_pk_bf16_f32 v112, v118, v119
	v_cvt_pk_bf16_f32 v113, v120, v121
	s_nop 0
	v_permlane32_swap_b32_e32 v102, v104
	v_permlane32_swap_b32_e32 v103, v105
	v_permlane32_swap_b32_e32 v106, v108
	v_permlane32_swap_b32_e32 v107, v109
	v_permlane32_swap_b32_e32 v110, v112
	v_permlane32_swap_b32_e32 v111, v113
	ds_read_b64_tr_b16 v[114:115], v193 offset:0
	ds_read_b64_tr_b16 v[116:117], v193 offset:0x800
	ds_read_b64_tr_b16 v[118:119], v193 offset:0x1000
	ds_read_b64_tr_b16 v[120:121], v193 offset:0x1800
	ds_read_b64_tr_b16 v[122:123], v193 offset:0x2000
	ds_read_b64_tr_b16 v[124:125], v193 offset:0x2800
	ds_read_b64_tr_b16 v[126:127], v193 offset:0x3000
	ds_read_b64_tr_b16 v[128:129], v193 offset:0x3800
	s_waitcnt lgkmcnt(0)
	s_nop 0
	v_mfma_f32_32x32x16_bf16 v[48:63], v[96:99], v[114:117], v[48:63]
	ds_read_b64_tr_b16 v[114:115], v193 offset:0x200
	ds_read_b64_tr_b16 v[116:117], v193 offset:0xa00
	v_mfma_f32_32x32x16_bf16 v[48:63], v[102:105], v[118:121], v[48:63]
	ds_read_b64_tr_b16 v[118:119], v193 offset:0x1200
	ds_read_b64_tr_b16 v[120:121], v193 offset:0x1a00
	v_mfma_f32_32x32x16_bf16 v[48:63], v[106:109], v[122:125], v[48:63]
	ds_read_b64_tr_b16 v[122:123], v193 offset:0x2200
	ds_read_b64_tr_b16 v[124:125], v193 offset:0x2a00
	v_mfma_f32_32x32x16_bf16 v[48:63], v[110:113], v[126:129], v[48:63]
	ds_read_b64_tr_b16 v[126:127], v193 offset:0x3200
	ds_read_b64_tr_b16 v[128:129], v193 offset:0x3a00
	s_waitcnt lgkmcnt(0)
	v_mfma_f32_32x32x16_bf16 v[32:47], v[96:99], v[114:117], v[32:47]
	ds_read_b64_tr_b16 v[114:115], v193 offset:0x400
	ds_read_b64_tr_b16 v[116:117], v193 offset:0xc00
	v_mfma_f32_32x32x16_bf16 v[32:47], v[102:105], v[118:121], v[32:47]
	ds_read_b64_tr_b16 v[118:119], v193 offset:0x1400
	ds_read_b64_tr_b16 v[120:121], v193 offset:0x1c00
	v_mfma_f32_32x32x16_bf16 v[32:47], v[106:109], v[122:125], v[32:47]
	ds_read_b64_tr_b16 v[122:123], v193 offset:0x2400
	ds_read_b64_tr_b16 v[124:125], v193 offset:0x2c00
	v_mfma_f32_32x32x16_bf16 v[32:47], v[110:113], v[126:129], v[32:47]
	ds_read_b64_tr_b16 v[126:127], v193 offset:0x3400
	ds_read_b64_tr_b16 v[128:129], v193 offset:0x3c00
	s_waitcnt lgkmcnt(0)
	v_mfma_f32_32x32x16_bf16 v[16:31], v[96:99], v[114:117], v[16:31]
	ds_read_b64_tr_b16 v[114:115], v193 offset:0x600
	ds_read_b64_tr_b16 v[116:117], v193 offset:0xe00
	v_mfma_f32_32x32x16_bf16 v[16:31], v[102:105], v[118:121], v[16:31]
	ds_read_b64_tr_b16 v[118:119], v193 offset:0x1600
	ds_read_b64_tr_b16 v[120:121], v193 offset:0x1e00
	v_mfma_f32_32x32x16_bf16 v[16:31], v[106:109], v[122:125], v[16:31]
	ds_read_b64_tr_b16 v[122:123], v193 offset:0x2600
	ds_read_b64_tr_b16 v[124:125], v193 offset:0x2e00
	v_mfma_f32_32x32x16_bf16 v[16:31], v[110:113], v[126:129], v[16:31]
	ds_read_b64_tr_b16 v[126:127], v193 offset:0x3600
	ds_read_b64_tr_b16 v[128:129], v193 offset:0x3e00
	s_waitcnt lgkmcnt(0)
	v_mfma_f32_32x32x16_bf16 v[0:15], v[96:99], v[114:117], v[0:15]
	v_mfma_f32_32x32x16_bf16 v[0:15], v[102:105], v[118:121], v[0:15]
	v_mfma_f32_32x32x16_bf16 v[0:15], v[106:109], v[122:125], v[0:15]
	v_mfma_f32_32x32x16_bf16 v[0:15], v[110:113], v[126:129], v[0:15]
	v_max_f32_e32 v96, v81, v81
	v_max_f32_e32 v97, v80, v80
	v_max_f32_e32 v96, v97, v96
	v_max3_f32 v96, v96, v82, v83
	v_max3_f32 v96, v96, v84, v85
	v_max3_f32 v96, v96, v86, v87
	v_max3_f32 v96, v96, v88, v89
	v_max3_f32 v96, v96, v90, v91
	v_max3_f32 v96, v96, v92, v93
	v_max3_f32 v96, v96, v94, v95
	v_max3_f32 v96, v96, v64, v65
	v_max3_f32 v96, v96, v66, v67
	v_max3_f32 v96, v96, v68, v69
	v_max3_f32 v96, v96, v70, v71
	v_max3_f32 v96, v96, v72, v73
	v_max3_f32 v96, v96, v74, v75
	v_max3_f32 v96, v96, v76, v77
	v_max3_f32 v96, v96, v78, v79
	v_mov_b32_e32 v97, v96
	s_nop 1
	v_permlane32_swap_b32_e32 v96, v97
	v_max_f32_e32 v97, v97, v97
	v_max_f32_e32 v96, v96, v96
	v_max_f32_e32 v96, v96, v97
	v_sub_f32_e32 v97, v96, v174
	v_cmp_ge_f32_e32 vcc, s93, v97
	v_max_f32_e32 v97, v174, v174
	v_max_f32_e32 v96, v97, v96
	v_sub_f32_e32 v97, v174, v96
	v_mul_f32_e32 v97, 0x3e0293ee, v97
	v_exp_f32_e32 v97, v97
	s_cmp_eq_u64 vcc, exec
	s_cselect_b64 s[6:7], -1, 0
	v_cndmask_b32_e64 v97, v97, 1.0, s[6:7]
	v_cmp_gt_f32_e32 vcc, 1.0, v97
	s_barrier
	s_cbranch_vccz .LBB0_755
	s_and_saveexec_b64 s[8:9], s[4:5]
	ds_write_b32 v194, v97 offset:128
	s_or_b64 exec, exec, s[8:9]
	s_waitcnt lgkmcnt(0)
	v_add_u32_e32 v98, v192, v144
	ds_read_b128 v[102:105], v98 offset:224
	ds_read_b128 v[106:109], v98 offset:192
	ds_read_b128 v[110:113], v98 offset:160
	ds_read_b128 v[114:117], v98 offset:128
	s_waitcnt lgkmcnt(3)
	v_pk_mul_f32 v[60:61], v[60:61], v[102:103]
	s_waitcnt lgkmcnt(2)
	v_pk_mul_f32 v[56:57], v[56:57], v[106:107]
	s_waitcnt lgkmcnt(1)
	v_pk_mul_f32 v[52:53], v[52:53], v[110:111]
	v_pk_mul_f32 v[62:63], v[62:63], v[104:105]
	v_pk_mul_f32 v[58:59], v[58:59], v[108:109]
	v_pk_mul_f32 v[54:55], v[54:55], v[112:113]
	s_waitcnt lgkmcnt(0)
	v_pk_mul_f32 v[50:51], v[50:51], v[116:117]
	v_pk_mul_f32 v[48:49], v[48:49], v[114:115]
	v_pk_mul_f32 v[44:45], v[44:45], v[102:103]
	v_pk_mul_f32 v[40:41], v[40:41], v[106:107]
	v_pk_mul_f32 v[36:37], v[36:37], v[110:111]
	v_pk_mul_f32 v[46:47], v[46:47], v[104:105]
	v_pk_mul_f32 v[42:43], v[42:43], v[108:109]
	v_pk_mul_f32 v[38:39], v[38:39], v[112:113]
	v_pk_mul_f32 v[34:35], v[34:35], v[116:117]
	v_pk_mul_f32 v[32:33], v[32:33], v[114:115]
	v_pk_mul_f32 v[28:29], v[28:29], v[102:103]
	v_pk_mul_f32 v[24:25], v[24:25], v[106:107]
	v_pk_mul_f32 v[20:21], v[20:21], v[110:111]
	v_pk_mul_f32 v[30:31], v[30:31], v[104:105]
	v_pk_mul_f32 v[26:27], v[26:27], v[108:109]
	v_pk_mul_f32 v[22:23], v[22:23], v[112:113]
	v_pk_mul_f32 v[18:19], v[18:19], v[116:117]
	v_pk_mul_f32 v[16:17], v[16:17], v[114:115]
	v_pk_mul_f32 v[12:13], v[12:13], v[102:103]
	v_pk_mul_f32 v[8:9], v[8:9], v[106:107]
	v_pk_mul_f32 v[4:5], v[4:5], v[110:111]
	v_pk_mul_f32 v[14:15], v[14:15], v[104:105]
	v_pk_mul_f32 v[10:11], v[10:11], v[108:109]
	v_pk_mul_f32 v[6:7], v[6:7], v[112:113]
	v_pk_mul_f32 v[2:3], v[2:3], v[116:117]
	v_pk_mul_f32 v[0:1], v[0:1], v[114:115]
